# v41 + attention slow-path QK: all 8 K-fragment LDS reads issued up front
# speedup vs baseline: 1.0340x; 1.0028x over previous
.Latt_slow:
	s_cmp_lt_i32 s95, s86
	s_cselect_b64 s[4:5], -1, 0
	s_and_b32 s6, s95, s89
	s_cmp_eq_u32 s6, s76
	s_cselect_b64 s[6:7], -1, 0
	s_and_b64 s[6:7], s[4:5], s[6:7]
	v_cndmask_b32_e64 v153, 0, 1, s[6:7]
	v_cmp_ne_u32_e64 s[4:5], 1, v153
	s_andn2_b64 vcc, exec, s[6:7]
	s_mov_b32 s71, s8
	s_cbranch_vccnz .LBB0_1306
	s_lshl_b32 s6, s71, 14
	v_add_u32_e32 v228, s6, v163
	v_add_u32_e32 v229, s6, v164
	v_add_u32_e32 v230, s6, v165
	v_add_u32_e32 v231, s6, v166
	ds_read_b128 v[96:99], v228
	ds_read_b128 v[112:115], v228 offset:8192
	ds_read_b128 v[200:203], v229
	ds_read_b128 v[216:219], v229 offset:8192
	ds_read_b128 v[204:207], v230
	ds_read_b128 v[220:223], v230 offset:8192
	ds_read_b128 v[208:211], v231
	ds_read_b128 v[224:227], v231 offset:8192
	s_waitcnt lgkmcnt(7)
	v_mfma_f32_32x32x16_bf16 v[96:111], v[96:99], v[132:135], 0
	s_waitcnt lgkmcnt(6)
	v_mfma_f32_32x32x16_bf16 v[112:127], v[112:115], v[132:135], 0
	s_waitcnt lgkmcnt(5)
	v_mfma_f32_32x32x16_bf16 v[96:111], v[200:203], v[136:139], v[96:111]
	s_waitcnt lgkmcnt(4)
	v_mfma_f32_32x32x16_bf16 v[112:127], v[216:219], v[136:139], v[112:127]
	s_waitcnt lgkmcnt(3)
	v_mfma_f32_32x32x16_bf16 v[96:111], v[204:207], v[140:143], v[96:111]
	s_waitcnt lgkmcnt(2)
	v_mfma_f32_32x32x16_bf16 v[112:127], v[220:223], v[140:143], v[112:127]
	s_waitcnt lgkmcnt(1)
	v_mfma_f32_32x32x16_bf16 v[96:111], v[208:211], v[144:147], v[96:111]
	s_waitcnt lgkmcnt(0)
	v_mfma_f32_32x32x16_bf16 v[112:127], v[224:227], v[144:147], v[112:127]
